# w_in phase: the 170 workgroups idle in round 2 run the last 170 attention-side w_in units formerly in the mixer queue
# baseline (speedup 1.0000x reference)
.LBB0_234:
	s_andn2_b64 vcc, exec, s[26:27]
	s_cbranch_vccnz .LBB0_236
	s_mul_i32 s22, s25, 0x66666667
	s_mul_hi_u32 s23, s24, 0x66666667
	s_mul_hi_u32 s21, s25, 0x66666667
	s_add_u32 s22, s22, s23
	s_mul_i32 s20, s24, 0x66666666
	s_addc_u32 s21, s21, 0
	s_mul_hi_u32 s5, s24, 0x66666666
	s_add_u32 s20, s20, s22
	s_addc_u32 s5, s5, 0
	s_add_u32 s5, s21, s5
	s_addc_u32 s20, 0, 0
	s_mul_i32 s22, s25, 0x66666666
	s_mul_hi_u32 s21, s25, 0x66666666
	s_add_u32 s5, s22, s5
	s_addc_u32 s21, s21, s20
	s_ashr_i32 s20, s25, 31
	s_mul_i32 s22, s20, 0x66666666
	s_mul_hi_u32 s23, s20, 0x66666667
	s_add_i32 s22, s23, s22
	s_mul_i32 s20, s20, 0x66666667
	s_add_i32 s22, s22, s20
	s_add_u32 s20, s5, s20
	s_addc_u32 s21, s21, s22
	s_lshr_b32 s5, s21, 31
	s_lshr_b64 s[20:21], s[20:21], 1
	s_add_i32 s20, s20, s5
	s_mul_i32 s5, s20, 5
	s_sub_i32 s5, s24, s5
	s_add_i32 s22, s5, 4
	s_branch .LBB0_236
.Lwsteal:
	s_cmp_lg_u32 s25, 0
	s_cbranch_scc1 .LBB0_236
	s_add_i32 s5, s24, 0xfffffeaa
	s_cmpk_lt_u32 s5, 0xaa
	s_cbranch_scc0 .LBB0_236
	s_add_i32 s5, s5, 0xd6
	s_mul_hi_u32 s20, s5, 0xaaaaaaab
	s_lshr_b32 s20, s20, 2
	s_mul_i32 s21, s20, 6
	s_sub_i32 s21, s5, s21
	s_add_i32 s5, s21, 5
	s_cmp_lt_u32 s21, 4
	s_cselect_b32 s22, s21, s5
	s_mov_b64 s[2:3], -1

.LBB0_671:
	s_or_b64 exec, exec, s[2:3]
	s_waitcnt vmcnt(0)
	v_readfirstlane_b32 s2, v2
	s_mov_b64 s[8:9], s[72:73]
	s_nop 0
	v_add_u32_e32 v0, s2, v0
	v_add_u32_e32 v2, 0xaa, v0
	v_cmp_lt_i32_e32 vcc, 0xd5, v0
	s_nop 1
	v_cndmask_b32_e32 v0, v0, v2, vcc
	v_cmp_gt_i32_e32 vcc, s62, v0
	v_cmp_le_i32_e64 s[2:3], s85, v0
	s_or_b64 s[4:5], vcc, s[2:3]
	s_nor_b64 s[10:11], s[4:5], s[72:73]
	s_and_saveexec_b64 s[4:5], s[10:11]
	s_cbranch_execz .LBB0_686
	s_mov_b32 s10, 0x1000000
	s_branch .LBB0_675

.LBB0_675:
	global_load_dword v2, v1, s[90:91] offset:192 sc1
	s_mov_b64 s[8:9], -1
	s_waitcnt vmcnt(0)
	v_cmp_lt_u32_e32 vcc, 0xd5, v2
	s_cbranch_vccnz .LBB0_674
	s_cmp_lg_u32 s10, 0
	s_sleep 2
	s_cbranch_scc0 .LBB0_673
	global_load_dword v2, v1, s[90:91] offset:192 sc1
	s_waitcnt vmcnt(0)
	v_cmp_gt_u32_e32 vcc, 0xd6, v2
	s_cbranch_vccz .LBB0_674
	s_sleep 2
	global_load_dword v2, v1, s[90:91] offset:192 sc1
	s_waitcnt vmcnt(0)
	v_cmp_gt_u32_e32 vcc, 0xd6, v2
	s_cbranch_vccz .LBB0_674
	s_sleep 2
	global_load_dword v2, v1, s[90:91] offset:192 sc1
	s_waitcnt vmcnt(0)
	v_cmp_gt_u32_e32 vcc, 0xd6, v2
	s_cbranch_vccz .LBB0_674
	s_sleep 2
	global_load_dword v2, v1, s[90:91] offset:192 sc1
	s_waitcnt vmcnt(0)
	v_cmp_gt_u32_e32 vcc, 0xd6, v2
	s_cbranch_vccz .LBB0_674
	s_sleep 2
	global_load_dword v2, v1, s[90:91] offset:192 sc1
	s_waitcnt vmcnt(0)
	v_cmp_gt_u32_e32 vcc, 0xd6, v2
	s_cbranch_vccz .LBB0_674
	s_sleep 2
	global_load_dword v2, v1, s[90:91] offset:192 sc1
	s_waitcnt vmcnt(0)
	v_cmp_gt_u32_e32 vcc, 0xd6, v2
	s_cbranch_vccz .LBB0_674
	s_sleep 2
	global_load_dword v2, v1, s[90:91] offset:192 sc1
	s_waitcnt vmcnt(0)
	v_cmp_gt_u32_e32 vcc, 0xd6, v2
	s_cbranch_vccz .LBB0_674
	s_sleep 2
	s_add_i32 s10, s10, -8
	s_mov_b64 s[8:9], 0
	s_branch .LBB0_674
